# combo28 + dn_prep last step (w / u^T tiles) as a two-deep LDS read pipeline with converts and stores behind the next tile's MFMAs
# speedup vs baseline: 1.0018x; 1.0018x over previous
; #define LAS __attribute__((address_space(3)))
; __device__ __forceinline__ unsigned cvt_pk_bf16(float lo, float hi) { const f32v2_t v = {lo, hi}; const bf16v2_t r = __builtin_convertvector(v, bf16v2_t); return __builtin_bit_cast(unsigned, r); }
; __device__ __forceinline__ f32x4 mfma16(const bf16x8& a, const bf16x8& b, const f32x4& c) { return __builtin_amdgcn_mfma_f32_16x16x32_bf16(a, b, c, 0, 0, 0); }
; __device__ __forceinline__ void dn_prep(const Params& p, LAS unsigned char* lds) {
;     ...
;         lds_barrier();
;         {
;             const int td = wid;
;             int z5; asm volatile("v_mov_b32 %0, 0" : "=v"(z5));
;             const int fr = ((tid + z5) & 15), fq = ((tid + z5) & 63) >> 4;
; #pragma unroll
;             for (int tt = 0; tt < 4; ++tt) {
;                 f32x4 au = {0.f, 0.f, 0.f, 0.f}, aw = {0.f, 0.f, 0.f, 0.f};
; #pragma unroll
;                 for (int kk = 0; kk < 2; ++kk) {
;                     const bf16x8 tu = *(const LAS bf16x8*)(Tu + (16 * tt + fr) * 72 + kk * 32 + 8 * fq), vt = *(const LAS bf16x8*)(Vts + (16 * td + fr) * 72 + ((kk * 32 + 8 * fq) ^ (8 * td)));
;                     au = mfma16(tu, vt, au);
;                     const bf16x8 kt = *(const LAS bf16x8*)(Kts + (16 * td + fr) * 72 + ((kk * 32 + 8 * fq) ^ (8 * td))), tw = *(const LAS bf16x8*)(Tw + (16 * tt + fr) * 72 + kk * 32 + 8 * fq);
;                     aw = mfma16(kt, tw, aw);
;                 }
;                 u32x2 wu; wu.x = cvt_pk_bf16(au[0], au[1]); wu.y = cvt_pk_bf16(au[2], au[3]);
;                 *(u32x2*)(gUT + (16 * td + fr) * 64 + 16 * tt + 4 * fq) = wu;
;                 u32x2 ww; ww.x = cvt_pk_bf16(aw[0], aw[1]); ww.y = cvt_pk_bf16(aw[2], aw[3]);
;                 *(u32x2*)(gW + (16 * tt + fr) * 128 + 32 * (td >> 1) + 8 * fq + 4 * (td & 1)) = ww;
;             }
; #pragma unroll
;             for (int q = tid + z5; q < 1024; q += 512) { const int dk = q >> 3, c8 = q & 7, u = c8 >> 2, f = c8 & 3;
;                 const int sw = 8 * ((dk >> 4) & 7);
;                 const u32x2 lo = *(const LAS u32x2*)(Kts + dk * 72 + ((32 * u + 4 * f) ^ sw)), hi = *(const LAS u32x2*)(Kts + dk * 72 + ((32 * u + 16 + 4 * f) ^ sw));
;                 *(u32x4*)(gKT + dk * 64 + 8 * c8) = (u32x4){lo.x, lo.y, hi.x, hi.y}; }
.LBB0_381:
	s_or_b64 exec, exec, s[24:25]
	s_lshl_b64 s[24:25], s[26:27], 1
	s_waitcnt lgkmcnt(0)
	s_barrier
	v_mov_b32 v0, 0
	s_add_u32 s0, s31, s24
	v_add_u32_e32 v20, v0, v184
	v_and_b32_e32 v21, 15, v20
	s_addc_u32 s1, s35, s25
	v_bfe_u32 v0, v20, 4, 2
	v_or_b32_e32 v1, v21, v156
	v_lshl_or_b32 v132, v21, 7, v226
	v_lshlrev_b32_e32 v30, 3, v0
	v_mul_u32_u24_e32 v1, 0x48, v1
	v_lshl_add_u64 v[2:3], s[0:1], 0, v[132:133]
	v_mov_b32_e32 v31, v133
	v_lshlrev_b32_e32 v0, 4, v0
	v_lshl_add_u32 v32, v1, 1, 0
	v_lshl_add_u64 v[18:19], v[2:3], 0, v[30:31]
	v_lshl_add_u64 v[2:3], v[134:135], 0, s[24:25]
	v_mov_b32_e32 v1, v133
	v_lshl_add_u64 v[2:3], v[2:3], 0, v[0:1]
	v_mul_u32_u24_e32 v1, 0x48, v21
	s_add_i32 s6, 0, 0x15c00
	v_lshlrev_b32_e32 v1, 1, v1
	s_add_i32 s7, 0, 0x18000
	v_mov_b32_e32 v139, v133
	v_add3_u32 v34, s6, v0, v1
	v_xor_b32_e32 v4, v30, v158
	s_waitcnt lgkmcnt(0)
	v_lshl_add_u64 v[16:17], v[2:3], 0, v[138:139]
	v_add3_u32 v35, s7, v0, v1
	v_lshl_add_u32 v4, v4, 1, v32
	v_bitop3_b32 v220, v30, v158, 32 bitop3:0x36
	v_lshl_add_u32 v220, v220, 1, v32
	ds_read_b128 v[12:15], v4 offset:53248
	ds_read_b128 v[8:11], v220 offset:53248
	ds_read_b128 v[0:3], v220 offset:34816
	ds_read_b128 v[4:7], v4 offset:34816
	ds_read_b128 v[176:179], v34
	ds_read_b128 v[180:183], v34 offset:64
	ds_read_b128 v[186:189], v35
	ds_read_b128 v[190:193], v35 offset:64
	ds_read_b128 v[194:197], v34 offset:2304
	ds_read_b128 v[198:201], v34 offset:2368
	ds_read_b128 v[202:205], v35 offset:2304
	ds_read_b128 v[206:209], v35 offset:2368
	v_lshlrev_b32_e32 v132, 8, v21
	s_waitcnt lgkmcnt(4)
	v_mfma_f32_16x16x32_bf16 v[22:25], v[176:179], v[12:15], 0
	v_mfma_f32_16x16x32_bf16 v[26:29], v[4:7], v[186:189], 0
	v_mfma_f32_16x16x32_bf16 v[22:25], v[180:183], v[8:11], v[22:25]
	v_mfma_f32_16x16x32_bf16 v[26:29], v[0:3], v[190:193], v[26:29]
	s_nop 4
	ds_read_b128 v[176:179], v34 offset:4608
	ds_read_b128 v[180:183], v34 offset:4672
	ds_read_b128 v[186:189], v35 offset:4608
	ds_read_b128 v[190:193], v35 offset:4672
	s_waitcnt lgkmcnt(4)
	v_mfma_f32_16x16x32_bf16 v[30:33], v[194:197], v[12:15], 0
	v_mfma_f32_16x16x32_bf16 v[210:213], v[4:7], v[202:205], 0
	v_mfma_f32_16x16x32_bf16 v[30:33], v[198:201], v[8:11], v[30:33]
	v_mfma_f32_16x16x32_bf16 v[210:213], v[0:3], v[206:209], v[210:213]
	v_cvt_pk_bf16_f32 v22, v22, v23
	v_cvt_pk_bf16_f32 v23, v24, v25
	global_store_dwordx2 v[18:19], v[22:23], off
	v_cvt_pk_bf16_f32 v26, v26, v27
	v_cvt_pk_bf16_f32 v27, v28, v29
	v_lshl_add_u64 v[218:219], v[16:17], 0, v[132:133]
	global_store_dwordx2 v[218:219], v[26:27], off
	ds_read_b128 v[194:197], v34 offset:6912
	ds_read_b128 v[198:201], v34 offset:6976
	ds_read_b128 v[202:205], v35 offset:6912
	ds_read_b128 v[206:209], v35 offset:6976
	s_waitcnt lgkmcnt(4)
	v_mfma_f32_16x16x32_bf16 v[22:25], v[176:179], v[12:15], 0
	v_mfma_f32_16x16x32_bf16 v[26:29], v[4:7], v[186:189], 0
	v_mfma_f32_16x16x32_bf16 v[22:25], v[180:183], v[8:11], v[22:25]
	v_mfma_f32_16x16x32_bf16 v[26:29], v[0:3], v[190:193], v[26:29]
	v_cvt_pk_bf16_f32 v30, v30, v31
	v_cvt_pk_bf16_f32 v31, v32, v33
	global_store_dwordx2 v[18:19], v[30:31], off offset:32
	v_cvt_pk_bf16_f32 v210, v210, v211
	v_cvt_pk_bf16_f32 v211, v212, v213
	v_or_b32_e32 v218, 0x1000, v132
	v_mov_b32_e32 v219, v133
	v_lshl_add_u64 v[218:219], v[16:17], 0, v[218:219]
	global_store_dwordx2 v[218:219], v[210:211], off
	s_waitcnt lgkmcnt(0)
	v_mfma_f32_16x16x32_bf16 v[30:33], v[194:197], v[12:15], 0
	v_mfma_f32_16x16x32_bf16 v[210:213], v[4:7], v[202:205], 0
	v_mfma_f32_16x16x32_bf16 v[30:33], v[198:201], v[8:11], v[30:33]
	v_mfma_f32_16x16x32_bf16 v[210:213], v[0:3], v[206:209], v[210:213]
	v_cvt_pk_bf16_f32 v22, v22, v23
	v_cvt_pk_bf16_f32 v23, v24, v25
	global_store_dwordx2 v[18:19], v[22:23], off offset:64
	v_cvt_pk_bf16_f32 v26, v26, v27
	v_cvt_pk_bf16_f32 v27, v28, v29
	v_or_b32_e32 v218, 0x2000, v132
	v_mov_b32_e32 v219, v133
	v_lshl_add_u64 v[218:219], v[16:17], 0, v[218:219]
	global_store_dwordx2 v[218:219], v[26:27], off
	s_nop 7
	v_cvt_pk_bf16_f32 v30, v30, v31
	v_cvt_pk_bf16_f32 v31, v32, v33
	global_store_dwordx2 v[18:19], v[30:31], off offset:96
	v_cvt_pk_bf16_f32 v210, v210, v211
	v_cvt_pk_bf16_f32 v211, v212, v213
	v_or_b32_e32 v218, 0x3000, v132
	v_mov_b32_e32 v219, v133
	v_lshl_add_u64 v[218:219], v[16:17], 0, v[218:219]
	global_store_dwordx2 v[218:219], v[210:211], off
	v_or_b32_e32 v132, 0x3000, v132
	s_movk_i32 s0, 0x400
	v_cmp_gt_i32_e32 vcc, s0, v20
	s_and_saveexec_b64 s[26:27], vcc
	s_cbranch_execz .LBB0_190
	v_readlane_b32 s0, v248, 10
	s_add_u32 s24, s0, s24
	v_readlane_b32 s0, v248, 11
	s_addc_u32 s25, s0, s25
	v_lshlrev_b32_e32 v0, 2, v20
	v_lshlrev_b32_e32 v1, 3, v20
	s_mov_b64 s[28:29], 0
